# XCD-local grid barrier (no L2 writeback, no cross-XCD step) before attention and z-GEMM phases, guarded by a blockIdx%8-to-XCC placement census; on top of DF epilogue rescheduling
# speedup vs baseline: 1.0069x; 1.0069x over previous
; #define LAS __attribute__((address_space(3)))
; #define LAS __attribute__((address_space(3)))
; __device__ __forceinline__ unsigned xb_add(unsigned* p, unsigned v) { return __hip_atomic_fetch_add(p, v, __ATOMIC_RELAXED, __HIP_MEMORY_SCOPE_AGENT); }
; __device__ __forceinline__ unsigned xb_xcc_id() { return (unsigned)__builtin_amdgcn_s_getreg((3 << 11) | 20) & 0xFu; }
; __device__ __forceinline__ XcdBarrier xcd_barrier_post(unsigned* bar, volatile LAS unsigned* st) {
;     XcdBarrier b; b.bar = bar; b.x = xb_xcc_id(); b.st = st;
;     if (threadIdx.x == 0) (void)xb_add(&bar[XB_XCNT(b.x)], 1u);
;     return b;
; }
; __global__ void __launch_bounds__(NWAVES * 64, 2) fwd(Params p) {
;     extern __shared__ __attribute__((aligned(16))) unsigned char lds_raw[];
;     LAS unsigned char* lds = (LAS unsigned char*)lds_raw;
;     cg::grid_group grid = cg::this_grid();
;     const int wave0 = __builtin_amdgcn_readfirstlane((int)threadIdx.x >> 6);
;     if (threadIdx.x < 16) ((LAS unsigned*)(lds + BARST_OFF))[threadIdx.x] = 0u;
;     __syncthreads();
;     XcdBarrier bar = xcd_barrier_post((unsigned*)p.ws, (volatile LAS unsigned*)(lds + BARST_OFF));
_Z3fwd6Params:
	s_load_dwordx16 s[72:87], s[0:1], 0x40
	s_load_dwordx2 s[94:95], s[0:1], 0x80
	s_add_u32 s4, s0, 0x90
	v_and_b32_e32 v1, 0x3ff, v0
	s_mov_b32 s92, s2
	s_addc_u32 s5, s1, 0
	v_readfirstlane_b32 s11, v1
	v_cmp_gt_u32_e32 vcc, 16, v1
	s_and_saveexec_b64 s[2:3], vcc
	v_lshl_add_u32 v2, v1, 2, 0
	v_add_u32_e32 v2, 0x20800, v2
	v_mov_b32_e32 v3, 0
	ds_write_b32 v2, v3
	s_or_b64 exec, exec, s[2:3]
	s_load_dwordx2 s[88:89], s[0:1], 0x90
	s_waitcnt lgkmcnt(0)
	s_barrier
	s_getreg_b32 s2, hwreg(HW_REG_XCC_ID, 0, 4)
	s_and_b32 s10, s2, 15
	v_cmp_eq_u32_e32 vcc, 0, v1
	s_and_saveexec_b64 s[2:3], vcc
	s_cbranch_execz .LBB0_5
	s_mov_b64 s[6:7], exec
	v_mbcnt_lo_u32_b32 v2, s6, 0
	v_mbcnt_hi_u32_b32 v2, s7, v2
	v_cmp_eq_u32_e32 vcc, 0, v2
	s_and_b64 s[8:9], exec, vcc
	s_mov_b64 exec, s[8:9]
	s_cbranch_execz .LBB0_5
	s_lshl_b32 s8, s10, 8
	s_bcnt1_i32_b64 s6, s[6:7]
	v_mov_b32_e32 v2, s8
	v_mov_b32_e32 v3, s6
	global_atomic_add v2, v3, s[86:87] offset:1024
	s_and_b32 s6, s92, 7
	s_lshl_b32 s6, s6, 8
	s_add_i32 s6, s6, 0x3800
	s_lshl_b32 s7, 1, s10
	v_mov_b32_e32 v4, s6
	v_mov_b32_e32 v5, s7
	global_atomic_or v4, v5, s[86:87]

; __device__ __forceinline__ unsigned xb_ld(unsigned* p)              { return __hip_atomic_load(p, __ATOMIC_RELAXED, __HIP_MEMORY_SCOPE_AGENT); }
; __device__ __forceinline__ unsigned xb_add(unsigned* p, unsigned v) { return __hip_atomic_fetch_add(p, v, __ATOMIC_RELAXED, __HIP_MEMORY_SCOPE_AGENT); }
; #define XB_SPIN(cond, bar) do { unsigned _sp = 0; while (cond) { __builtin_amdgcn_s_sleep(1); \
;     if ((++_sp & 255u) == 0u) { if (xb_ld(&(bar)[XB_TMO])) break; if (_sp > XB_SPIN_CAP) { atomicAdd(&(bar)[XB_TMO], 1u); break; } } } } while (0)
; __device__ __forceinline__ void xcd_barrier(const XcdBarrier& b, bool leader) {
;     asm volatile("s_waitcnt vmcnt(0)" ::: "memory");
;     __syncthreads();
;     if (leader) {
;         unsigned* bar = b.bar;
;         __builtin_amdgcn_s_waitcnt(0);
;         unsigned nloc = b.st[0], nx = b.st[1];
;         if (nloc == 0u) { xcd_barrier_complete(bar, b.x, nloc, nx); b.st[0] = nloc; b.st[1] = nx; }
;         const unsigned old = xb_add(&bar[XB_XSUB(b.x)], 1u);
;         const unsigned gen = old / nloc;
;         if (old + 1u == (gen + 1u) * nloc) {
;             __builtin_amdgcn_fence(__ATOMIC_RELEASE, "agent");
;             asm volatile("s_waitcnt vmcnt(0)" ::: "memory");
;             const unsigned og = xb_add(&bar[XB_TOP], 1u);
;             const unsigned tg = og / nx;
;             if (og + 1u == (tg + 1u) * nx) xb_add(&bar[XB_TOPGEN], 1u);
;             else XB_SPIN(xb_ld(&bar[XB_TOPGEN]) == tg, bar);
;             __builtin_amdgcn_fence(__ATOMIC_ACQUIRE, "agent");
;             xb_add(&bar[XB_XGEN(b.x)], 1u);
;             asm volatile("s_waitcnt vmcnt(0)" ::: "memory");
;         } else {
;             XB_SPIN(xb_ld(&bar[XB_XGEN(b.x)]) == gen, bar);
;             __builtin_amdgcn_fence(__ATOMIC_ACQUIRE, "agent");
;             asm volatile("s_waitcnt vmcnt(0)" ::: "memory");
;         }
;     }
.LBB0_56:
	s_andn2_saveexec_b64 s[6:7], s[6:7]
	s_cbranch_execz .LBB0_76
	s_mov_b64 s[6:7], exec
	v_readlane_b32 s8, v255, 11
	s_cmp_eq_u32 s8, 3
	s_cselect_b32 s9, 1, 0
	s_cmp_eq_u32 s8, 4
	s_cselect_b32 s9, 1, s9
	s_cmp_eq_u32 s9, 0
	s_cbranch_scc1 .Lxb_global
	v_mov_b32_e32 v8, 0x20808
	ds_read_b32 v9, v8
	s_waitcnt lgkmcnt(0)
	v_readfirstlane_b32 s8, v9
	s_cmp_lg_u32 s8, 0
	s_cbranch_scc1 .Lxb_have
	v_mov_b32_e32 v8, 0x3800
	global_load_dword v9, v8, s[86:87] offset:0 sc1
	global_load_dword v10, v8, s[86:87] offset:256 sc1
	global_load_dword v11, v8, s[86:87] offset:512 sc1
	global_load_dword v12, v8, s[86:87] offset:768 sc1
	global_load_dword v13, v8, s[86:87] offset:1024 sc1
	global_load_dword v14, v8, s[86:87] offset:1280 sc1
	global_load_dword v15, v8, s[86:87] offset:1536 sc1
	global_load_dword v16, v8, s[86:87] offset:1792 sc1
	s_waitcnt vmcnt(0)
	s_mov_b32 s8, 1
	v_readfirstlane_b32 s9, v9
	s_bcnt1_i32_b32 s9, s9
	s_cmp_eq_u32 s9, 1
	s_cselect_b32 s8, s8, 2
	v_readfirstlane_b32 s9, v10
	s_bcnt1_i32_b32 s9, s9
	s_cmp_eq_u32 s9, 1
	s_cselect_b32 s8, s8, 2
	v_readfirstlane_b32 s9, v11
	s_bcnt1_i32_b32 s9, s9
	s_cmp_eq_u32 s9, 1
	s_cselect_b32 s8, s8, 2
	v_readfirstlane_b32 s9, v12
	s_bcnt1_i32_b32 s9, s9
	s_cmp_eq_u32 s9, 1
	s_cselect_b32 s8, s8, 2
	v_readfirstlane_b32 s9, v13
	s_bcnt1_i32_b32 s9, s9
	s_cmp_eq_u32 s9, 1
	s_cselect_b32 s8, s8, 2
	v_readfirstlane_b32 s9, v14
	s_bcnt1_i32_b32 s9, s9
	s_cmp_eq_u32 s9, 1
	s_cselect_b32 s8, s8, 2
	v_readfirstlane_b32 s9, v15
	s_bcnt1_i32_b32 s9, s9
	s_cmp_eq_u32 s9, 1
	s_cselect_b32 s8, s8, 2
	v_readfirstlane_b32 s9, v16
	s_bcnt1_i32_b32 s9, s9
	s_cmp_eq_u32 s9, 1
	s_cselect_b32 s8, s8, 2
	v_mov_b32_e32 v8, 0x20808
	v_mov_b32_e32 v9, s8
	ds_write_b32 v8, v9
	s_waitcnt lgkmcnt(0)
.Lxb_have:
	s_cmp_eq_u32 s8, 1
	s_cbranch_scc1 .LBB0_73
.Lxb_global:
	buffer_wbl2 sc1
	s_waitcnt lgkmcnt(0)
	s_waitcnt vmcnt(0)
	v_mbcnt_lo_u32_b32 v0, s6, 0
	v_mbcnt_hi_u32_b32 v0, s7, v0
	v_cmp_eq_u32_e32 vcc, 0, v0
	s_and_saveexec_b64 s[8:9], vcc
	s_cbranch_execz .LBB0_59
	s_bcnt1_i32_b64 s6, s[6:7]
	v_mov_b32_e32 v3, s6
	v_readlane_b32 s6, v253, 41
	v_readlane_b32 s7, v253, 42
	s_nop 4
	global_atomic_add v3, v1, v3, s[6:7] sc0
